# packed v_pk_mul_f32 among MFMAs split into two v_mul_f32 (attention O rescale, scan state decay), bit-identical
# speedup vs baseline: 1.0233x; 1.0233x over previous
; __device__ __forceinline__ void scan_gate(const LAS unsigned char* raw, ScanSt& st, LAS unsigned char* buf, float lb, int w, int l16, int g) {
;     ...
;     for (int j = 0; j < 4; ++j) { const float x = bf2f(rf[j]); const float sg = __builtin_amdgcn_rcpf(1.0f + __builtin_amdgcn_exp2f(-x * L2E));
;         const float f = lb + (1.0f - lb) * sg; kk[j] = (1.0f - lb) * (1.0f - sg); run += __builtin_amdgcn_logf(f); cs[j] = run; qv[j] = bf2f(rq[j]); }
;     const float T = run, t1 = __shfl_xor(T, 16), t2 = __shfl_xor(T, 32), t3 = __shfl_xor(t1, 32);
;     const float E = g == 0 ? 0.f : (g == 1 ? t1 : (g == 2 ? (t2 + t3) : (t1 + t2 + t3))), blast = (T + t1) + (t2 + t3);
;     float qd[4], ki[4], ks[4]; const float dec = __builtin_amdgcn_exp2f(blast);
;     float fq_[4], ib[4];
; #pragma unroll
;     for (int j = 0; j < 4; ++j) { const float bj = E + cs[j]; qd[j] = qv[j] * __builtin_amdgcn_exp2f(bj); fq_[j] = 1.0f - kk[j]; }
;     ib[3] = __builtin_amdgcn_exp2f(-(E + cs[3])); ib[2] = ib[3] * fq_[3]; ib[1] = ib[2] * fq_[2]; ib[0] = ib[1] * fq_[1];
; #pragma unroll
;     for (int j = 0; j < 4; ++j) { ki[j] = kk[j] * ib[j]; ks[j] = ki[j] * dec; }
;     const int colb = (16 * w + l16) * 2;
;     const unsigned q01 = cvtpk(qd[0], qd[1]), q23 = cvtpk(qd[2], qd[3]), k01 = cvtpk(ki[0], ki[1]), k23 = cvtpk(ki[2], ki[3]);
;     LAS unsigned char* qp = buf + SC_QD + (4 * g) * SC_RS + colb; LAS unsigned char* kp = buf + SC_KI + (4 * g) * SC_RS + colb;
;     *(LAS unsigned short*)(qp) = (unsigned short)(q01 & 0xffffu); *(LAS unsigned short*)(qp + SC_RS) = (unsigned short)(q01 >> 16);
;     *(LAS unsigned short*)(qp + 2 * SC_RS) = (unsigned short)(q23 & 0xffffu); *(LAS unsigned short*)(qp + 3 * SC_RS) = (unsigned short)(q23 >> 16);
;     *(LAS unsigned short*)(kp) = (unsigned short)(k01 & 0xffffu); *(LAS unsigned short*)(kp + SC_RS) = (unsigned short)(k01 >> 16);
;     *(LAS unsigned short*)(kp + 2 * SC_RS) = (unsigned short)(k23 & 0xffffu); *(LAS unsigned short*)(kp + 3 * SC_RS) = (unsigned short)(k23 >> 16);
;     *(LAS u32x2*)(buf + SC_KST + (16 * w + l16) * 32 + 8 * g) = (u32x2){cvtpk(ks[0], ks[1]), cvtpk(ks[2], ks[3])};
;     if (g == 0) *(LAS float*)(buf + SC_DEC + (16 * w + l16) * 4) = dec;
;     st.vf = __builtin_bit_cast(s16x4, (u32x2){rv[0] | (rv[1] << 16), rv[2] | (rv[3] << 16)});
; #pragma unroll
;     for (int j = 0; j < 4; ++j) st.gv[j] = bf2f(rg[j]);
; }
.LBB0_409:
	s_or_b64 exec, exec, s[56:57]
	v_lshlrev_b32_e32 v66, 16, v59
	v_lshlrev_b32_e32 v59, 16, v0
	v_add_f32_e32 v0, v63, v64
	v_exp_f32_e32 v68, v0
	v_add_f32_e32 v0, v62, v64
	v_exp_f32_e32 v69, v0
	v_add_f32_e32 v0, v61, v64
	s_waitcnt lgkmcnt(0)
	v_pk_add_f32 v[56:57], v[52:53], v[56:57]
	v_exp_f32_e32 v52, v0
	v_add_f32_e32 v0, v53, v64
	v_exp_f32_e32 v53, v0
	v_lshlrev_b32_e32 v58, 16, v58
	v_pk_add_f32 v[54:55], v[54:55], 1.0 op_sel_hi:[1,0] neg_lo:[1,0] neg_hi:[1,0]
	v_pk_add_f32 v[2:3], v[2:3], 1.0 op_sel_hi:[1,0] neg_lo:[1,0] neg_hi:[1,0]
	v_pk_mul_f32 v[52:53], v[52:53], v[58:59]
	v_exp_f32_e64 v59, -v0
	v_pk_mul_f32 v[54:55], v[126:127], v[54:55]
	v_add_f32_e32 v0, v56, v57
	v_sub_f32_e32 v58, 1.0, v55
	v_pk_mul_f32 v[2:3], v[126:127], v[2:3]
	v_sub_f32_e32 v63, 1.0, v54
	v_exp_f32_e32 v0, v0
	v_mul_f32_e32 v58, v58, v59
	v_sub_f32_e32 v62, 1.0, v3
	v_mul_f32_e32 v57, v63, v58
	v_lshlrev_b32_e32 v67, 16, v60
	v_mul_f32_e32 v56, v62, v57
	v_pk_mul_f32 v[60:61], v[68:69], v[66:67]
	v_pk_mul_f32 v[2:3], v[2:3], v[56:57]
	v_pk_mul_f32 v[54:55], v[54:55], v[58:59]
	v_pk_mul_f32 v[56:57], v[0:1], v[2:3] op_sel_hi:[0,1]
	v_pk_mul_f32 v[58:59], v[0:1], v[54:55] op_sel_hi:[0,1]
	v_cvt_pk_bf16_f32 v60, v60, v61
	v_cvt_pk_bf16_f32 v52, v52, v53
	v_cvt_pk_bf16_f32 v2, v2, v3
	v_cvt_pk_bf16_f32 v3, v54, v55
	v_add_u32_e32 v53, v149, v143
	ds_write_b16 v53, v60 offset:16384
	ds_write_b16_d16_hi v53, v60 offset:16656
	ds_write_b16 v53, v52 offset:16928
	ds_write_b16_d16_hi v53, v52 offset:17200
	ds_write_b16 v53, v2 offset:20736
	ds_write_b16_d16_hi v53, v2 offset:21008
	ds_write_b16 v53, v3 offset:21280
	ds_write_b16_d16_hi v53, v3 offset:21552
	v_cvt_pk_bf16_f32 v2, v56, v57
	v_cvt_pk_bf16_f32 v3, v58, v59
	ds_write_b64 v164, v[2:3] offset:25088
	s_and_saveexec_b64 s[56:57], s[0:1]
	ds_write_b32 v155, v0 offset:29184
	s_or_b64 exec, exec, s[56:57]
	ds_read2_b64 v[52:55], v177 offset0:32 offset1:36
	ds_read2_b64 v[56:59], v156 offset1:4
	ds_read2_b64 v[60:63], v177 offset0:40 offset1:44
	ds_read2_b64 v[64:67], v156 offset0:8 offset1:12
	ds_read2_b64 v[68:71], v177 offset0:48 offset1:52
	v_mov_b32_e32 v0, s43
	s_waitcnt lgkmcnt(3)
	v_mfma_f32_16x16x32_bf16 v[52:55], v[52:55], v[56:59], 0
	s_waitcnt lgkmcnt(1)
	v_mfma_f32_16x16x32_bf16 v[52:55], v[60:63], v[64:67], v[52:55]
	ds_read2_b64 v[60:63], v156 offset0:16 offset1:20
	ds_read2_b64 v[72:75], v156 offset0:24 offset1:28
	ds_read2_b64 v[76:79], v177 offset0:56 offset1:60
	ds_read2st64_b64 v[80:83], v157 offset0:17 offset1:18
	s_waitcnt lgkmcnt(3)
	v_mfma_f32_16x16x32_bf16 v[52:55], v[68:71], v[60:63], v[52:55]
	ds_read_b128 v[68:71], v148 offset:12800
	v_mfma_f32_16x16x32_bf16 v[56:59], v[56:59], v[96:99], 0
	s_waitcnt lgkmcnt(2)
	v_mfma_f32_16x16x32_bf16 v[52:55], v[76:79], v[72:75], v[52:55]
	v_mfma_f32_16x16x32_bf16 v[56:59], v[64:67], v[92:95], v[56:59]
	ds_read_b128 v[64:67], v148 offset:12864
	s_nop 5
	v_cndmask_b32_e64 v0, v52, v0, s[6:7]
	v_cndmask_b32_e64 v2, 0, v53, s[8:9]
	v_cndmask_b32_e64 v3, v54, 0, s[10:11]
	v_cndmask_b32_e64 v53, v55, 0, s[12:13]
	v_cndmask_b32_e64 v0, v0, v52, s[8:9]
	v_cvt_pk_bf16_f32 v3, v3, v53
	v_mfma_f32_16x16x32_bf16 v[52:55], v[60:63], v[88:91], v[56:59]
	v_cvt_pk_bf16_f32 v2, v0, v2
	s_waitcnt lgkmcnt(0)
	v_mul_f32_e32 v30, v30, v66
	v_mul_f32_e32 v31, v31, v67
	v_mul_f32_e32 v28, v28, v64
	v_mul_f32_e32 v29, v29, v65
	v_mfma_f32_16x16x32_bf16 v[52:55], v[72:75], v[84:87], v[52:55]
	v_mul_f32_e64 v22, v22, v70
	v_mul_f32_e64 v23, v23, v71
	v_mul_f32_e32 v20, v20, v68
	v_mul_f32_e32 v21, v21, v69
	ds_read_b128 v[56:59], v148 offset:12928
	ds_read_b128 v[60:63], v148 offset:12992
	ds_read2st64_b64 v[68:71], v157 offset0:19 offset1:20
	v_mfma_f32_16x16x16_bf16 v[64:67], v[82:83], v[130:131], v[28:31]
	s_waitcnt lgkmcnt(1)
	v_mul_f32_e32 v34, v34, v62
	v_mul_f32_e32 v35, v35, v63
	s_nop 0
	ds_read2st64_b64 v[28:31], v157 offset0:21 offset1:22
	v_mfma_f32_16x16x16_bf16 v[100:103], v[2:3], v[130:131], v[52:55]
	v_mul_f32_e64 v32, v32, v60
	v_mul_f32_e64 v33, v33, v61
	ds_read_b128 v[60:63], v148 offset:13120
	v_mul_f32_e32 v26, v26, v58
	v_mul_f32_e32 v27, v27, v59
	v_mfma_f32_16x16x16_bf16 v[52:55], v[80:81], v[130:131], v[20:23]
	v_mul_f32_e64 v24, v24, v56
	v_mul_f32_e64 v25, v25, v57
	s_nop 0
	ds_read_b128 v[20:23], v148 offset:13056
	s_waitcnt lgkmcnt(3)
	v_mfma_f32_16x16x16_bf16 v[56:59], v[68:69], v[130:131], v[24:27]
	s_waitcnt lgkmcnt(0)
	v_mul_f32_e32 v22, v38, v22
	v_mul_f32_e32 v23, v39, v23
	v_mul_f32_e32 v20, v36, v20
	v_mul_f32_e32 v21, v37, v21
	ds_read2st64_b64 v[36:39], v157 offset0:23 offset1:24
	v_mul_f32_e32 v26, v42, v62
	v_mul_f32_e32 v27, v43, v63
	v_mfma_f32_16x16x16_bf16 v[72:75], v[28:29], v[130:131], v[20:23]
	v_mul_f32_e64 v24, v40, v60
	v_mul_f32_e64 v25, v41, v61
	s_waitcnt lgkmcnt(1)
	v_mfma_f32_16x16x16_bf16 v[60:63], v[70:71], v[130:131], v[32:35]
	s_nop 1
	ds_read_b128 v[32:35], v148 offset:13184
	ds_read_b128 v[40:43], v148 offset:13248
	s_waitcnt lgkmcnt(1)
	v_mul_f32_e32 v22, v46, v34
	v_mul_f32_e32 v23, v47, v35
	v_mfma_f32_16x16x16_bf16 v[68:71], v[30:31], v[130:131], v[24:27]
	s_nop 2
	v_mul_f32_e32 v20, v44, v32
	v_mul_f32_e32 v21, v45, v33
	s_waitcnt lgkmcnt(0)
	s_nop 0
	v_mfma_f32_16x16x16_bf16 v[76:79], v[36:37], v[130:131], v[20:23]
	v_mul_f32_e64 v28, v50, v42
	v_mul_f32_e64 v29, v51, v43
	v_mul_f32_e32 v26, v48, v40
	v_mul_f32_e32 v27, v49, v41
	s_waitcnt lgkmcnt(0)
	s_nop 0
	v_mfma_f32_16x16x16_bf16 v[80:83], v[38:39], v[130:131], v[26:29]
	v_mul_f32_e32 v20, v100, v100
	v_mul_f32_e32 v21, v101, v101
	v_mul_f32_e32 v22, v102, v102
	v_mul_f32_e32 v23, v103, v103
	s_nop 1
	v_add_f32_dpp v20, v20, v20 row_ror:1 row_mask:0xf bank_mask:0xf
	v_add_f32_dpp v21, v21, v21 row_ror:1 row_mask:0xf bank_mask:0xf
	v_add_f32_dpp v22, v22, v22 row_ror:1 row_mask:0xf bank_mask:0xf
	v_add_f32_dpp v23, v23, v23 row_ror:1 row_mask:0xf bank_mask:0xf
	v_add_f32_dpp v20, v20, v20 row_ror:2 row_mask:0xf bank_mask:0xf
	v_add_f32_dpp v21, v21, v21 row_ror:2 row_mask:0xf bank_mask:0xf
	v_add_f32_dpp v22, v22, v22 row_ror:2 row_mask:0xf bank_mask:0xf
	v_add_f32_dpp v23, v23, v23 row_ror:2 row_mask:0xf bank_mask:0xf
	v_add_f32_dpp v20, v20, v20 row_ror:4 row_mask:0xf bank_mask:0xf
	v_add_f32_dpp v21, v21, v21 row_ror:4 row_mask:0xf bank_mask:0xf
	v_add_f32_dpp v22, v22, v22 row_ror:4 row_mask:0xf bank_mask:0xf
	v_add_f32_dpp v23, v23, v23 row_ror:4 row_mask:0xf bank_mask:0xf
	v_add_f32_dpp v20, v20, v20 row_ror:8 row_mask:0xf bank_mask:0xf
	v_add_f32_dpp v21, v21, v21 row_ror:8 row_mask:0xf bank_mask:0xf
	v_add_f32_dpp v22, v22, v22 row_ror:8 row_mask:0xf bank_mask:0xf
	v_add_f32_dpp v23, v23, v23 row_ror:8 row_mask:0xf bank_mask:0xf
	s_and_saveexec_b64 s[56:57], s[14:15]
	s_cbranch_execz .LBB0_413
	s_waitcnt lgkmcnt(0)
	v_add_u32_e32 v0, s3, v147
	ds_write_b128 v0, v[20:23] offset:13312

; #define LAS __attribute__((address_space(3)))
; __device__ __forceinline__ unsigned cvtpk(float lo, float hi) { return pg8::cvt_pk_bf16(lo, hi); }
; __device__ __forceinline__ void scan_gate(const LAS unsigned char* raw, ScanSt& st, LAS unsigned char* buf, float lb, int w, int l16, int g) {
;     ...
;     for (int j = 0; j < 4; ++j) { const float bj = E + cs[j]; qd[j] = qv[j] * __builtin_amdgcn_exp2f(bj); fq_[j] = 1.0f - kk[j]; }
;     ib[3] = __builtin_amdgcn_exp2f(-(E + cs[3])); ib[2] = ib[3] * fq_[3]; ib[1] = ib[2] * fq_[2]; ib[0] = ib[1] * fq_[1];
; #pragma unroll
;     for (int j = 0; j < 4; ++j) { ki[j] = kk[j] * ib[j]; ks[j] = ki[j] * dec; }
;     const int colb = (16 * w + l16) * 2;
;     const unsigned q01 = cvtpk(qd[0], qd[1]), q23 = cvtpk(qd[2], qd[3]), k01 = cvtpk(ki[0], ki[1]), k23 = cvtpk(ki[2], ki[3]);
;     LAS unsigned char* qp = buf + SC_QD + (4 * g) * SC_RS + colb; LAS unsigned char* kp = buf + SC_KI + (4 * g) * SC_RS + colb;
;     *(LAS unsigned short*)(qp) = (unsigned short)(q01 & 0xffffu); *(LAS unsigned short*)(qp + SC_RS) = (unsigned short)(q01 >> 16);
;     *(LAS unsigned short*)(qp + 2 * SC_RS) = (unsigned short)(q23 & 0xffffu); *(LAS unsigned short*)(qp + 3 * SC_RS) = (unsigned short)(q23 >> 16);
;     *(LAS unsigned short*)(kp) = (unsigned short)(k01 & 0xffffu); *(LAS unsigned short*)(kp + SC_RS) = (unsigned short)(k01 >> 16);
;     *(LAS unsigned short*)(kp + 2 * SC_RS) = (unsigned short)(k23 & 0xffffu); *(LAS unsigned short*)(kp + 3 * SC_RS) = (unsigned short)(k23 >> 16);
;     *(LAS u32x2*)(buf + SC_KST + (16 * w + l16) * 32 + 8 * g) = (u32x2){cvtpk(ks[0], ks[1]), cvtpk(ks[2], ks[3])};
;     if (g == 0) *(LAS float*)(buf + SC_DEC + (16 * w + l16) * 4) = dec;
;     st.vf = __builtin_bit_cast(s16x4, (u32x2){rv[0] | (rv[1] << 16), rv[2] | (rv[3] << 16)});
; #pragma unroll
;     for (int j = 0; j < 4; ++j) st.gv[j] = bf2f(rg[j]);
; }
; __device__ __forceinline__ bf16x8 cat44(const s16x4 a, const s16x4 b) { return (bf16x8){a[0], a[1], a[2], a[3], b[0], b[1], b[2], b[3]}; }
; __device__ __forceinline__ void scan_mma(f32x4 (&St)[8], const ScanSt& st, f32x4& o, LAS unsigned char* buf, int w, int l16, int g) {
;     const LAS unsigned char* qp = buf + SC_QD + l16 * SC_RS + 8 * g; const LAS unsigned char* kp = buf + SC_KI + l16 * SC_RS + 8 * g;
;     bf16x8 qd[4], ki[4];
; #pragma unroll
.LBB0_439:
	s_or_b64 exec, exec, s[54:55]
	v_lshlrev_b32_e32 v36, 16, v29
	v_lshlrev_b32_e32 v29, 16, v0
	v_add_f32_e32 v0, v33, v34
	v_exp_f32_e32 v38, v0
	v_add_f32_e32 v0, v32, v34
	v_exp_f32_e32 v39, v0
	v_add_f32_e32 v0, v31, v34
	s_waitcnt lgkmcnt(0)
	v_pk_add_f32 v[26:27], v[22:23], v[26:27]
	v_exp_f32_e32 v22, v0
	v_add_f32_e32 v0, v23, v34
	v_exp_f32_e32 v23, v0
	v_lshlrev_b32_e32 v28, 16, v28
	v_pk_add_f32 v[24:25], v[24:25], 1.0 op_sel_hi:[1,0] neg_lo:[1,0] neg_hi:[1,0]
	v_pk_add_f32 v[20:21], v[20:21], 1.0 op_sel_hi:[1,0] neg_lo:[1,0] neg_hi:[1,0]
	v_pk_mul_f32 v[22:23], v[22:23], v[28:29]
	v_exp_f32_e64 v29, -v0
	v_pk_mul_f32 v[24:25], v[126:127], v[24:25]
	v_add_f32_e32 v0, v26, v27
	v_sub_f32_e32 v28, 1.0, v25
	v_pk_mul_f32 v[20:21], v[126:127], v[20:21]
	v_sub_f32_e32 v33, 1.0, v24
	v_exp_f32_e32 v0, v0
	v_mul_f32_e32 v28, v28, v29
	v_sub_f32_e32 v32, 1.0, v21
	v_mul_f32_e32 v27, v33, v28
	v_lshlrev_b32_e32 v37, 16, v30
	v_mul_f32_e32 v26, v32, v27
	v_pk_mul_f32 v[30:31], v[38:39], v[36:37]
	v_pk_mul_f32 v[20:21], v[20:21], v[26:27]
	v_pk_mul_f32 v[24:25], v[24:25], v[28:29]
	v_pk_mul_f32 v[26:27], v[0:1], v[20:21] op_sel_hi:[0,1]
	v_pk_mul_f32 v[28:29], v[0:1], v[24:25] op_sel_hi:[0,1]
	v_cvt_pk_bf16_f32 v30, v30, v31
	v_cvt_pk_bf16_f32 v20, v20, v21
	v_cvt_pk_bf16_f32 v21, v24, v25
	v_cvt_pk_bf16_f32 v22, v22, v23
	ds_write_b16 v163, v30
	ds_write_b16_d16_hi v163, v30 offset:272
	ds_write_b16 v163, v22 offset:544
	ds_write_b16_d16_hi v163, v22 offset:816
	ds_write_b16 v163, v20 offset:4352
	ds_write_b16_d16_hi v163, v20 offset:4624
	ds_write_b16 v163, v21 offset:4896
	ds_write_b16_d16_hi v163, v21 offset:5168
	v_cvt_pk_bf16_f32 v20, v26, v27
	v_cvt_pk_bf16_f32 v21, v28, v29
	ds_write_b64 v164, v[20:21] offset:8704
	s_and_saveexec_b64 s[54:55], s[0:1]
	ds_write_b32 v155, v0 offset:12800
	s_or_b64 exec, exec, s[54:55]
	ds_read2_b64 v[20:23], v179 offset0:32 offset1:36
	ds_read2_b64 v[24:27], v178 offset1:4
	ds_read2_b64 v[28:31], v179 offset0:40 offset1:44
	ds_read2_b64 v[32:35], v178 offset0:8 offset1:12
	ds_read2_b64 v[36:39], v179 offset0:48 offset1:52
	v_mov_b32_e32 v0, s43
	s_waitcnt lgkmcnt(3)
	v_mfma_f32_16x16x32_bf16 v[20:23], v[20:23], v[24:27], 0
	s_waitcnt lgkmcnt(1)
	v_mfma_f32_16x16x32_bf16 v[20:23], v[28:31], v[32:35], v[20:23]
	ds_read2_b64 v[28:31], v178 offset0:16 offset1:20
	ds_read2_b64 v[40:43], v178 offset0:24 offset1:28
	ds_read2_b64 v[44:47], v179 offset0:56 offset1:60
	ds_read2st64_b64 v[48:51], v157 offset0:49 offset1:50
	s_waitcnt lgkmcnt(3)
	v_mfma_f32_16x16x32_bf16 v[20:23], v[36:39], v[28:31], v[20:23]
	ds_read_b128 v[36:39], v177 offset:29184
	v_mfma_f32_16x16x32_bf16 v[24:27], v[24:27], v[96:99], 0
	s_waitcnt lgkmcnt(2)
	v_mfma_f32_16x16x32_bf16 v[20:23], v[44:47], v[40:43], v[20:23]
	v_mfma_f32_16x16x32_bf16 v[24:27], v[32:35], v[92:95], v[24:27]
	ds_read_b128 v[32:35], v177 offset:29248
	s_nop 5
	v_cndmask_b32_e64 v0, v20, v0, s[6:7]
	v_cndmask_b32_e64 v44, 0, v21, s[8:9]
	v_cndmask_b32_e64 v21, v22, 0, s[10:11]
	v_cndmask_b32_e64 v22, v23, 0, s[12:13]
	v_cndmask_b32_e64 v0, v0, v20, s[8:9]
	v_cvt_pk_bf16_f32 v45, v21, v22
	v_mfma_f32_16x16x32_bf16 v[20:23], v[28:31], v[88:91], v[24:27]
	v_cvt_pk_bf16_f32 v44, v0, v44
	ds_read_b128 v[28:31], v177 offset:29312
	s_waitcnt lgkmcnt(2)
	v_mul_f32_e32 v38, v54, v38
	v_mul_f32_e32 v39, v55, v39
	v_mfma_f32_16x16x32_bf16 v[20:23], v[40:43], v[84:87], v[20:23]
	v_mul_f32_e64 v36, v52, v36
	v_mul_f32_e64 v37, v53, v37
	s_waitcnt lgkmcnt(1)
	v_mul_f32_e32 v24, v64, v32
	v_mul_f32_e32 v25, v65, v33
	v_mul_f32_e32 v26, v66, v34
	v_mul_f32_e32 v27, v67, v35
	ds_read_b128 v[32:35], v177 offset:29376
	ds_read2st64_b64 v[40:43], v157 offset0:51 offset1:52
	v_mfma_f32_16x16x16_bf16 v[100:103], v[44:45], v[2:3], v[20:23]
	s_waitcnt lgkmcnt(2)
	v_mul_f32_e32 v44, v56, v28
	v_mul_f32_e32 v45, v57, v29
	v_mul_f32_e32 v46, v58, v30
	v_mul_f32_e32 v47, v59, v31
	ds_read_b128 v[52:55], v177 offset:29504
	v_mfma_f32_16x16x16_bf16 v[20:23], v[48:49], v[2:3], v[36:39]
	s_waitcnt lgkmcnt(2)
	v_mul_f32_e32 v32, v60, v32
	v_mul_f32_e32 v33, v61, v33
	v_mul_f32_e32 v34, v62, v34
	v_mul_f32_e32 v35, v63, v35
	v_mfma_f32_16x16x16_bf16 v[28:31], v[50:51], v[2:3], v[24:27]
	ds_read2st64_b64 v[48:51], v157 offset0:53 offset1:54
	ds_read2st64_b64 v[58:61], v157 offset0:55 offset1:56
	ds_read_b128 v[36:39], v177 offset:29440
	s_waitcnt lgkmcnt(4)
	v_mfma_f32_16x16x16_bf16 v[24:27], v[40:41], v[2:3], v[44:47]
	s_waitcnt lgkmcnt(0)
	v_mul_f32_e32 v36, v72, v36
	v_mul_f32_e32 v37, v73, v37
	v_mul_f32_e32 v38, v74, v38
	v_mul_f32_e32 v39, v75, v39
	v_mul_f32_e32 v44, v68, v52
	v_mul_f32_e32 v45, v69, v53
	v_mul_f32_e32 v46, v70, v54
	v_mul_f32_e32 v47, v71, v55
	v_mfma_f32_16x16x16_bf16 v[32:35], v[42:43], v[2:3], v[32:35]
	ds_read_b128 v[52:55], v177 offset:29568
	ds_read_b128 v[62:65], v177 offset:29632
	v_mfma_f32_16x16x16_bf16 v[36:39], v[48:49], v[2:3], v[36:39]
	s_waitcnt lgkmcnt(0)
	v_mfma_f32_16x16x16_bf16 v[40:43], v[50:51], v[2:3], v[44:47]
	s_nop 0
	v_mul_f32_e32 v44, v76, v52
	v_mul_f32_e32 v45, v77, v53
	s_waitcnt lgkmcnt(0)
	v_mul_f32_e32 v46, v78, v54
	v_mul_f32_e32 v47, v79, v55
	s_waitcnt lgkmcnt(0)
	s_nop 0
	v_mfma_f32_16x16x16_bf16 v[44:47], v[58:59], v[2:3], v[44:47]
	s_waitcnt lgkmcnt(0)
	v_mul_f32_e32 v50, v82, v64
	v_mul_f32_e32 v51, v83, v65
	v_mul_f32_e32 v48, v80, v62
	v_mul_f32_e32 v49, v81, v63
	s_waitcnt lgkmcnt(0)
	s_nop 0
	v_mfma_f32_16x16x16_bf16 v[48:51], v[60:61], v[2:3], v[48:51]
	v_mul_f32_e32 v54, v100, v100
	v_mul_f32_e32 v55, v101, v101
	v_mul_f32_e32 v56, v102, v102
	v_mul_f32_e32 v57, v103, v103
	s_nop 1
	v_add_f32_dpp v54, v54, v54 row_ror:1 row_mask:0xf bank_mask:0xf
	v_add_f32_dpp v55, v55, v55 row_ror:1 row_mask:0xf bank_mask:0xf
	v_add_f32_dpp v56, v56, v56 row_ror:1 row_mask:0xf bank_mask:0xf
	v_add_f32_dpp v57, v57, v57 row_ror:1 row_mask:0xf bank_mask:0xf
	v_add_f32_dpp v54, v54, v54 row_ror:2 row_mask:0xf bank_mask:0xf
	v_add_f32_dpp v55, v55, v55 row_ror:2 row_mask:0xf bank_mask:0xf
	v_add_f32_dpp v56, v56, v56 row_ror:2 row_mask:0xf bank_mask:0xf
	v_add_f32_dpp v57, v57, v57 row_ror:2 row_mask:0xf bank_mask:0xf
	v_add_f32_dpp v54, v54, v54 row_ror:4 row_mask:0xf bank_mask:0xf
	v_add_f32_dpp v55, v55, v55 row_ror:4 row_mask:0xf bank_mask:0xf
	v_add_f32_dpp v56, v56, v56 row_ror:4 row_mask:0xf bank_mask:0xf
	v_add_f32_dpp v57, v57, v57 row_ror:4 row_mask:0xf bank_mask:0xf
	v_add_f32_dpp v54, v54, v54 row_ror:8 row_mask:0xf bank_mask:0xf
	v_add_f32_dpp v55, v55, v55 row_ror:8 row_mask:0xf bank_mask:0xf
	v_add_f32_dpp v56, v56, v56 row_ror:8 row_mask:0xf bank_mask:0xf
	v_add_f32_dpp v57, v57, v57 row_ror:8 row_mask:0xf bank_mask:0xf
	s_and_saveexec_b64 s[54:55], s[14:15]
	s_cbranch_execz .LBB0_443
	s_waitcnt lgkmcnt(0)
	v_add_u32_e32 v0, s3, v147
	ds_write_b128 v0, v[54:57] offset:29696

; __device__ __forceinline__ void attn_phase(const Params& p, LAS unsigned char* lds) {
;     ...
;                 float rm = p0[0];
; #pragma unroll
;                 for (int r = 1; r < 16; ++r) rm = fmaxf(rm, p0[r]);
; #pragma unroll
;                 for (int r = 0; r < 16; ++r) rm = fmaxf(rm, p1[r]);
;                 rm = fmaxf(rm, __shfl_xor(rm, 32));
;                 const float mn = fmaxf(mrun, rm), alpha = __builtin_amdgcn_exp2f(mrun - mn); mrun = mn;
;                 float ps = 0.f;
; #pragma unroll
;                 for (int r = 0; r < 16; ++r) { p0[r] = __builtin_amdgcn_exp2f(p0[r] - mn); p1[r] = __builtin_amdgcn_exp2f(p1[r] - mn); ps += p0[r] + p1[r]; }
;                 lrun = lrun * alpha + ps;
;                 if (__any(alpha != 1.0f)) {
; #pragma unroll
;                     for (int d = 0; d < 4; ++d) o[d] *= alpha; }
.LBB0_648:
	s_nop 0
	v_max_f32_e32 v246, v65, v65
	v_max_f32_e32 v248, v64, v64
	v_max_f32_e32 v246, v248, v246
	v_max3_f32 v246, v246, v66, v67
	v_max3_f32 v246, v246, v68, v69
	v_max3_f32 v246, v246, v70, v71
	v_max3_f32 v246, v246, v72, v73
	v_max3_f32 v246, v246, v74, v75
	v_max3_f32 v246, v246, v76, v77
	v_max3_f32 v246, v246, v78, v79
	v_max3_f32 v246, v246, v80, v81
	v_max3_f32 v246, v246, v82, v83
	v_max3_f32 v246, v246, v84, v85
	v_max3_f32 v246, v246, v86, v87
	v_max3_f32 v246, v246, v88, v89
	v_max3_f32 v246, v246, v90, v91
	v_max3_f32 v246, v246, v92, v93
	v_max3_f32 v246, v246, v94, v95
	ds_bpermute_b32 v248, v241, v246
	s_waitcnt lgkmcnt(0)
	v_max3_f32 v246, v182, v246, v248
	v_sub_f32_e32 v182, v182, v246
	v_exp_f32_e32 v182, v182
	s_nop 0
	v_cmp_neq_f32_e32 vcc, 1.0, v182
	s_cbranch_vccz .LBB0_650
	v_mul_f32_e32 v62, v62, v182
	v_mul_f32_e32 v63, v63, v182
	v_mul_f32_e32 v60, v60, v182
	v_mul_f32_e32 v61, v61, v182
	v_mul_f32_e32 v58, v58, v182
	v_mul_f32_e32 v59, v59, v182
	v_mul_f32_e32 v56, v56, v182
	v_mul_f32_e32 v57, v57, v182
	v_mul_f32_e32 v54, v54, v182
	v_mul_f32_e32 v55, v55, v182
	v_mul_f32_e32 v52, v52, v182
	v_mul_f32_e32 v53, v53, v182
	v_mul_f32_e32 v50, v50, v182
	v_mul_f32_e32 v51, v51, v182
	v_mul_f32_e32 v48, v48, v182
	v_mul_f32_e32 v49, v49, v182
	v_mul_f32_e32 v46, v46, v182
	v_mul_f32_e32 v47, v47, v182
	v_mul_f32_e32 v44, v44, v182
	v_mul_f32_e32 v45, v45, v182
	v_mul_f32_e32 v42, v42, v182
	v_mul_f32_e32 v43, v43, v182
	v_mul_f32_e32 v40, v40, v182
	v_mul_f32_e32 v41, v41, v182
	v_mul_f32_e32 v38, v38, v182
	v_mul_f32_e32 v39, v39, v182
	v_mul_f32_e32 v36, v36, v182
	v_mul_f32_e32 v37, v37, v182
	v_mul_f32_e32 v34, v34, v182
	v_mul_f32_e32 v35, v35, v182
	v_mul_f32_e32 v32, v32, v182
	v_mul_f32_e32 v33, v33, v182
	v_mul_f32_e32 v30, v30, v182
	v_mul_f32_e32 v31, v31, v182
	v_mul_f32_e32 v28, v28, v182
	v_mul_f32_e32 v29, v29, v182
	v_mul_f32_e32 v26, v26, v182
	v_mul_f32_e32 v27, v27, v182
	v_mul_f32_e32 v24, v24, v182
	v_mul_f32_e32 v25, v25, v182
	v_mul_f32_e32 v22, v22, v182
	v_mul_f32_e32 v23, v23, v182
	v_mul_f32_e32 v20, v20, v182
	v_mul_f32_e32 v21, v21, v182
	v_mul_f32_e32 v18, v18, v182
	v_mul_f32_e32 v19, v19, v182
	v_mul_f32_e32 v16, v16, v182
	v_mul_f32_e32 v17, v17, v182
	v_mul_f32_e32 v14, v14, v182
	v_mul_f32_e32 v15, v15, v182
	v_mul_f32_e32 v12, v12, v182
	v_mul_f32_e32 v13, v13, v182
	v_mul_f32_e32 v10, v10, v182
	v_mul_f32_e32 v11, v11, v182
	v_mul_f32_e32 v8, v8, v182
	v_mul_f32_e32 v9, v9, v182
	v_mul_f32_e32 v6, v6, v182
	v_mul_f32_e32 v7, v7, v182
	v_mul_f32_e32 v4, v4, v182
	v_mul_f32_e32 v5, v5, v182
	v_mul_f32_e32 v2, v2, v182
	v_mul_f32_e32 v3, v3, v182
	v_mul_f32_e32 v0, v0, v182
	v_mul_f32_e32 v1, v1, v182
